# attention: late softmax exps redirected to free VGPRs and hoisted into the QK MFMA shadow with all 32 row-sum adds
# baseline (speedup 1.0000x reference)
; __device__ __forceinline__ void finishSM(f32x16& p0, f32x16& p1, float alpha, float& l_reg, bf16x8& pa0, bf16x8& pa1, bf16x8& pa2, bf16x8& pa3) {
; #pragma unroll
;     for (int r = 0; r < 16; ++r) p1[r] = __builtin_amdgcn_exp2f(p1[r]);
;     float ps = 0;
; #pragma unroll
;     for (int r = 0; r < 16; ++r) ps += p0[r];
; #pragma unroll
;     for (int r = 0; r < 16; ++r) ps += p1[r];
;     { auto rr = __builtin_amdgcn_permlane32_swap(__float_as_uint(ps), __float_as_uint(ps), false, false);
;       ps = __uint_as_float(rr[0]) + __uint_as_float(rr[1]); }
;     l_reg = l_reg * alpha + ps;
;     ...
;     PK4(p0, 0, pa0); PK4(p0, 8, pa1); PK4(p1, 0, pa2); PK4(p1, 8, pa3);
;     ...
; }
; template <int KB>
; __device__ __forceinline__ void qkt(f32x16& p0, f32x16& p1, const char* K_lds, int r32, int hi, const bf16x8* qr, const char* qbase) {
;     p0 = f32x16{}; p1 = f32x16{};
;     const char* kbp = K_lds + KB * SHM_K + r32 * KROW + hi * 16;
; #pragma unroll
;     for (int d0 = 0; d0 < 12; ++d0) { const char* a = kbp + d0 * 32;
;         bf16x8 b0 = *reinterpret_cast<const bf16x8*>(a);
;         bf16x8 b1 = *reinterpret_cast<const bf16x8*>(a + 32 * KROW);
;         const bf16x8 qf = d0 < 4 ? qr[d0 & 3] : *reinterpret_cast<const bf16x8*>(qbase + (d0 - 4) * 32);
;         p0 = __builtin_amdgcn_mfma_f32_32x32x16_bf16(b0, qf, p0, 0, 0, 0);
;         p1 = __builtin_amdgcn_mfma_f32_32x32x16_bf16(b1, qf, p1, 0, 0, 0); }
; }
.LBB0_1481:
	ds_read_b128 v[64:67], v202 offset:58368
	s_waitcnt vmcnt(0)
	ds_read_b128 v[100:103], v202 offset:58400
	v_add_u32_e32 v254, s31, v183
	v_add_u32_e32 v250, 0x80, v254
	v_min_u32_e32 v252, 0x100f, v250
	v_add_u32_e32 v251, 0x4080, v254
	v_add_u32_e32 v252, s14, v252
	v_cmp_gt_i32_e32 vcc, 16, v250
	s_nop 1
	v_cndmask_b32_e32 v250, v252, v251, vcc
	v_ashrrev_i32_e32 v251, 31, v250
	v_mad_i64_i32 v[252:253], s[0:1], v250, s33, v[184:185]
	v_lshlrev_b64 v[250:251], 12, v[250:251]
	v_lshl_add_u64 v[250:251], v[186:187], 0, v[250:251]
	global_load_dwordx4 v[146:149], v[250:251], off offset:128
	global_load_dwordx4 v[150:153], v[252:253], off
	global_load_dwordx4 v[154:157], v[252:253], off offset:128
	global_load_dwordx4 v[162:165], v[250:251], off
	global_load_dwordx4 v[158:161], v[252:253], off offset:256
	v_exp_f32_e32 v112, v172
	v_exp_f32_e32 v113, v173
	v_exp_f32_e32 v114, v170
	s_waitcnt lgkmcnt(1)
	v_mfma_f32_32x32x16_bf16 v[84:99], v[64:67], v[142:145], 0
	ds_read_b128 v[64:67], v206 offset:12800
	ds_read_b128 v[104:107], v206 offset:12832
	v_exp_f32_e32 v115, v171
	v_exp_f32_e32 v116, v168
	v_exp_f32_e32 v117, v169
	v_exp_f32_e32 v118, v166
	v_exp_f32_e32 v119, v167
	s_waitcnt lgkmcnt(1)
	v_mfma_f32_32x32x16_bf16 v[68:83], v[64:67], v[142:145], 0
	v_mfma_f32_32x32x16_bf16 v[84:99], v[100:103], v[138:141], v[84:99]
	ds_read_b128 v[64:67], v202 offset:58432
	ds_read_b128 v[100:103], v206 offset:12864
	v_exp_f32_e32 v250, v180
	v_exp_f32_e32 v251, v181
	v_exp_f32_e32 v252, v178
	s_waitcnt lgkmcnt(2)
	v_mfma_f32_32x32x16_bf16 v[68:83], v[104:107], v[138:141], v[68:83]
	v_exp_f32_e32 v253, v179
	v_add_f32_e32 v255, 0, v233
	v_add_f32_e32 v255, v235, v255
	s_waitcnt lgkmcnt(1)
	v_mfma_f32_32x32x16_bf16 v[84:99], v[64:67], v[134:137], v[84:99]
	v_add_f32_e32 v255, v231, v255
	v_add_f32_e32 v255, v234, v255
	v_add_f32_e32 v255, v223, v255
	s_waitcnt lgkmcnt(0)
	v_mfma_f32_32x32x16_bf16 v[68:83], v[100:103], v[134:137], v[68:83]
	ds_read_b128 v[64:67], v202 offset:58464
	ds_read_b128 v[100:103], v206 offset:12896
	v_add_f32_e32 v255, v232, v255
	v_add_f32_e32 v255, v221, v255
	v_add_f32_e32 v255, v222, v255
	s_waitcnt lgkmcnt(1)
	v_mfma_f32_32x32x16_bf16 v[84:99], v[64:67], v[130:133], v[84:99]
	v_add_f32_e32 v255, v217, v255
	v_add_f32_e32 v255, v220, v255
	v_add_f32_e32 v255, v215, v255
	s_waitcnt lgkmcnt(0)
	v_mfma_f32_32x32x16_bf16 v[68:83], v[100:103], v[130:133], v[68:83]
	ds_read_b128 v[64:67], v202 offset:58496
	ds_read_b128 v[100:103], v206 offset:12928
	ds_read_b128 v[104:107], v201
	ds_read_b128 v[108:111], v201 offset:32
	v_add_f32_e32 v255, v218, v255
	v_add_f32_e32 v255, v213, v255
	v_add_f32_e32 v255, v219, v255
	s_waitcnt lgkmcnt(1)
	v_mfma_f32_32x32x16_bf16 v[84:99], v[64:67], v[104:107], v[84:99]
	v_mfma_f32_32x32x16_bf16 v[68:83], v[100:103], v[104:107], v[68:83]
	ds_read_b128 v[64:67], v202 offset:58528
	ds_read_b128 v[100:103], v206 offset:12960
	v_add_f32_e32 v255, v214, v255
	v_add_f32_e32 v255, v216, v255
	v_add_f32_e32 v255, v112, v255
	s_waitcnt lgkmcnt(1)
	v_mfma_f32_32x32x16_bf16 v[84:99], v[64:67], v[108:111], v[84:99]
	v_add_f32_e32 v255, v113, v255
	v_add_f32_e32 v255, v114, v255
	v_add_f32_e32 v255, v115, v255
	s_waitcnt lgkmcnt(0)
	v_mfma_f32_32x32x16_bf16 v[68:83], v[100:103], v[108:111], v[68:83]
	ds_read_b128 v[64:67], v202 offset:58560
	ds_read_b128 v[100:103], v206 offset:12992
	ds_read_b128 v[104:107], v201 offset:64
	v_exp_f32_e32 v108, v176
	v_exp_f32_e32 v109, v177
	v_exp_f32_e32 v110, v174
	v_exp_f32_e32 v111, v175
	v_add_f32_e32 v255, v116, v255
	v_add_f32_e32 v255, v117, v255
	v_add_f32_e32 v255, v118, v255
	s_waitcnt lgkmcnt(0)
	v_mfma_f32_32x32x16_bf16 v[84:99], v[64:67], v[104:107], v[84:99]
	v_mfma_f32_32x32x16_bf16 v[68:83], v[100:103], v[104:107], v[68:83]
	ds_read_b128 v[64:67], v202 offset:58592
	ds_read_b128 v[100:103], v206 offset:13024
	ds_read_b128 v[104:107], v201 offset:96
	v_add_f32_e32 v255, v119, v255
	v_add_f32_e32 v255, v250, v255
	v_add_f32_e32 v255, v251, v255
	s_waitcnt lgkmcnt(0)
	v_mfma_f32_32x32x16_bf16 v[84:99], v[64:67], v[104:107], v[84:99]
	v_mfma_f32_32x32x16_bf16 v[68:83], v[100:103], v[104:107], v[68:83]
	ds_read_b128 v[64:67], v202 offset:58624
	ds_read_b128 v[100:103], v206 offset:13056
	ds_read_b128 v[104:107], v201 offset:128
	v_add_f32_e32 v255, v252, v255
	v_add_f32_e32 v255, v253, v255
	v_add_f32_e32 v255, v108, v255
	s_waitcnt lgkmcnt(0)
	v_mfma_f32_32x32x16_bf16 v[84:99], v[64:67], v[104:107], v[84:99]
	v_mfma_f32_32x32x16_bf16 v[68:83], v[100:103], v[104:107], v[68:83]
	ds_read_b128 v[64:67], v202 offset:58656
	ds_read_b128 v[100:103], v206 offset:13088
	ds_read_b128 v[104:107], v201 offset:160
	v_add_f32_e32 v255, v109, v255
	v_add_f32_e32 v255, v110, v255
	v_add_f32_e32 v210, v111, v255
	s_waitcnt lgkmcnt(0)
	v_mfma_f32_32x32x16_bf16 v[84:99], v[64:67], v[104:107], v[84:99]
	v_mfma_f32_32x32x16_bf16 v[68:83], v[100:103], v[104:107], v[68:83]
	ds_read_b128 v[64:67], v202 offset:58688
	ds_read_b128 v[100:103], v206 offset:13120
	ds_read_b128 v[104:107], v201 offset:192
	s_waitcnt lgkmcnt(0)
	v_mfma_f32_32x32x16_bf16 v[84:99], v[64:67], v[104:107], v[84:99]
	v_mfma_f32_32x32x16_bf16 v[68:83], v[100:103], v[104:107], v[68:83]
	ds_read_b128 v[64:67], v202 offset:58720
	ds_read_b128 v[100:103], v206 offset:13152
	ds_read_b128 v[104:107], v201 offset:224
	s_waitcnt lgkmcnt(0)
	v_mfma_f32_32x32x16_bf16 v[84:99], v[64:67], v[104:107], v[84:99]
	v_mfma_f32_32x32x16_bf16 v[68:83], v[100:103], v[104:107], v[68:83]
	v_mov_b32_e32 v211, v210
	s_nop 1
	v_permlane32_swap_b32_e32 v210, v211
	v_cvt_pk_bf16_f32 v64, v233, v235
	v_cvt_pk_bf16_f32 v65, v231, v234
	v_cvt_pk_bf16_f32 v66, v223, v232
	v_cvt_pk_bf16_f32 v67, v221, v222
	v_cvt_pk_bf16_f32 v100, v217, v220
	v_cvt_pk_bf16_f32 v101, v215, v218
	v_cvt_pk_bf16_f32 v102, v213, v219
	v_cvt_pk_bf16_f32 v103, v214, v216
	v_cvt_pk_bf16_f32 v104, v250, v251
	v_cvt_pk_bf16_f32 v105, v252, v253
	v_cvt_pk_bf16_f32 v106, v108, v109
	v_cvt_pk_bf16_f32 v107, v110, v111
	v_cvt_pk_bf16_f32 v108, v112, v113
	v_cvt_pk_bf16_f32 v109, v114, v115
	v_cvt_pk_bf16_f32 v110, v116, v117
	v_cvt_pk_bf16_f32 v111, v118, v119
	s_nop 0
	v_permlane32_swap_b32_e32 v64, v66
	v_permlane32_swap_b32_e32 v65, v67
	v_permlane32_swap_b32_e32 v100, v102
	v_permlane32_swap_b32_e32 v101, v103
	v_permlane32_swap_b32_e32 v104, v106
	v_permlane32_swap_b32_e32 v105, v107
	v_permlane32_swap_b32_e32 v108, v110
	v_permlane32_swap_b32_e32 v109, v111
	s_add_i32 s0, s31, 0x7f
	s_cmp_le_i32 s0, s30
	s_cbranch_scc1 .La_pvmax1
; __device__ __forceinline__ void mask_tile(f32x16& p0, f32x16& p1, int dq) {
;     const float NEG = -__builtin_inff();
; #pragma unroll
;     for (int r = 0; r < 16; ++r) {
;         const int c = (r & 3) + 8 * (r >> 2);
;         if (dq - c < 0) p0[r] = NEG;
;         if (dq - c - 32 < 0) p1[r] = NEG;
;     }
; }
; template <int VB>
; __device__ __forceinline__ void pv_tile(f32x16* o, int vb0, bf16x8 pa0, bf16x8 pa1, bf16x8 pa2, bf16x8 pa3) {
;     ...
;     PV_D0(0); PV_D0(1); PV_D0(2); PV_D0(3);
	ds_read_b64_tr_b16 v[112:113], v199 offset:0
	ds_read_b64_tr_b16 v[114:115], v199 offset:0x800
	ds_read_b64_tr_b16 v[116:117], v199 offset:0x1000
	ds_read_b64_tr_b16 v[118:119], v199 offset:0x1800
	ds_read_b64_tr_b16 v[120:121], v199 offset:0x2000
	ds_read_b64_tr_b16 v[122:123], v199 offset:0x2800
	ds_read_b64_tr_b16 v[124:125], v199 offset:0x3000
	ds_read_b64_tr_b16 v[126:127], v199 offset:0x3800
	s_waitcnt lgkmcnt(0)
	s_nop 0
	v_mfma_f32_32x32x16_bf16 v[48:63], v[64:67], v[112:115], v[48:63]
	ds_read_b64_tr_b16 v[112:113], v199 offset:0x200
	ds_read_b64_tr_b16 v[114:115], v199 offset:0xa00
	v_mfma_f32_32x32x16_bf16 v[48:63], v[100:103], v[116:119], v[48:63]
	ds_read_b64_tr_b16 v[116:117], v199 offset:0x1200
	ds_read_b64_tr_b16 v[118:119], v199 offset:0x1a00
	v_mfma_f32_32x32x16_bf16 v[48:63], v[104:107], v[120:123], v[48:63]
	ds_read_b64_tr_b16 v[120:121], v199 offset:0x2200
	ds_read_b64_tr_b16 v[122:123], v199 offset:0x2a00
	v_mfma_f32_32x32x16_bf16 v[48:63], v[108:111], v[124:127], v[48:63]
	ds_read_b64_tr_b16 v[124:125], v199 offset:0x3200
	ds_read_b64_tr_b16 v[126:127], v199 offset:0x3a00
	s_waitcnt lgkmcnt(0)
	v_mfma_f32_32x32x16_bf16 v[32:47], v[64:67], v[112:115], v[32:47]
	ds_read_b64_tr_b16 v[112:113], v199 offset:0x400
	ds_read_b64_tr_b16 v[114:115], v199 offset:0xc00
	v_mfma_f32_32x32x16_bf16 v[32:47], v[100:103], v[116:119], v[32:47]
	ds_read_b64_tr_b16 v[116:117], v199 offset:0x1400
	ds_read_b64_tr_b16 v[118:119], v199 offset:0x1c00
	v_mfma_f32_32x32x16_bf16 v[32:47], v[104:107], v[120:123], v[32:47]
	ds_read_b64_tr_b16 v[120:121], v199 offset:0x2400
	ds_read_b64_tr_b16 v[122:123], v199 offset:0x2c00
	v_mfma_f32_32x32x16_bf16 v[32:47], v[108:111], v[124:127], v[32:47]
	ds_read_b64_tr_b16 v[124:125], v199 offset:0x3400
	ds_read_b64_tr_b16 v[126:127], v199 offset:0x3c00
	s_waitcnt lgkmcnt(0)
	v_mfma_f32_32x32x16_bf16 v[16:31], v[64:67], v[112:115], v[16:31]
	ds_read_b64_tr_b16 v[112:113], v199 offset:0x600
	ds_read_b64_tr_b16 v[114:115], v199 offset:0xe00
	v_mfma_f32_32x32x16_bf16 v[16:31], v[100:103], v[116:119], v[16:31]
	ds_read_b64_tr_b16 v[116:117], v199 offset:0x1600
	ds_read_b64_tr_b16 v[118:119], v199 offset:0x1e00
	v_mfma_f32_32x32x16_bf16 v[16:31], v[104:107], v[120:123], v[16:31]
	ds_read_b64_tr_b16 v[120:121], v199 offset:0x2600
	ds_read_b64_tr_b16 v[122:123], v199 offset:0x2e00
	v_mfma_f32_32x32x16_bf16 v[16:31], v[108:111], v[124:127], v[16:31]
	ds_read_b64_tr_b16 v[124:125], v199 offset:0x3600
	ds_read_b64_tr_b16 v[126:127], v199 offset:0x3e00
	s_waitcnt lgkmcnt(0)
	v_mfma_f32_32x32x16_bf16 v[0:15], v[64:67], v[112:115], v[0:15]
	s_add_i32 s0, s31, 0x7f
	s_cmp_le_i32 s0, s30
	v_mfma_f32_32x32x16_bf16 v[0:15], v[100:103], v[116:119], v[0:15]
	v_mfma_f32_32x32x16_bf16 v[0:15], v[104:107], v[120:123], v[0:15]
	v_mfma_f32_32x32x16_bf16 v[0:15], v[108:111], v[124:127], v[0:15]
	s_cbranch_scc1 .LBB0_1483
	v_add_u32_e32 v64, 64, v209
	v_cmp_gt_i32_e64 s[96:97], 26, v64
	v_cmp_gt_i32_e32 vcc, 27, v64
	v_cmp_gt_i32_e64 s[94:95], 25, v64
	v_cmp_gt_i32_e64 s[92:93], 24, v64
	v_cndmask_b32_e32 v99, v99, v228, vcc
	s_and_b64 vcc, vcc, s[96:97]
	v_cndmask_b32_e32 v98, v98, v228, vcc
	s_and_b64 vcc, vcc, s[94:95]
	v_cmp_gt_i32_e64 s[90:91], 19, v64
	v_cndmask_b32_e32 v97, v97, v228, vcc
	s_and_b64 vcc, vcc, s[92:93]
	v_cmp_gt_i32_e64 s[88:89], 18, v64
	v_cndmask_b32_e32 v96, v96, v228, vcc
	s_and_b64 vcc, vcc, s[90:91]
	v_cmp_gt_i32_e64 s[86:87], 17, v64
	v_cndmask_b32_e32 v95, v95, v228, vcc
	s_and_b64 vcc, vcc, s[88:89]
	v_cmp_gt_i32_e64 s[84:85], 16, v64
	v_cndmask_b32_e32 v94, v94, v228, vcc
	s_and_b64 vcc, vcc, s[86:87]
	v_cmp_gt_i32_e64 s[82:83], 11, v64
	v_cndmask_b32_e32 v93, v93, v228, vcc
	s_and_b64 vcc, vcc, s[84:85]
	v_cmp_gt_i32_e64 s[80:81], 10, v64
	v_cndmask_b32_e32 v92, v92, v228, vcc
	s_and_b64 vcc, vcc, s[82:83]
	v_cmp_gt_i32_e64 s[78:79], 9, v64
	v_cndmask_b32_e32 v91, v91, v228, vcc
	s_and_b64 vcc, vcc, s[80:81]
	v_cmp_gt_i32_e64 s[76:77], 8, v64
	v_cndmask_b32_e32 v90, v90, v228, vcc
	s_and_b64 vcc, vcc, s[78:79]
	v_cmp_gt_i32_e64 s[74:75], 3, v64
	v_cndmask_b32_e32 v89, v89, v228, vcc
	s_and_b64 vcc, vcc, s[76:77]
	v_cmp_gt_i32_e64 s[72:73], 2, v64
	v_cndmask_b32_e32 v88, v88, v228, vcc
	s_and_b64 vcc, vcc, s[74:75]
	v_cmp_gt_i32_e64 s[70:71], 1, v64
	v_cndmask_b32_e32 v87, v87, v228, vcc
	s_and_b64 vcc, vcc, s[72:73]
	v_cmp_gt_i32_e64 s[4:5], 0, v64
	v_cndmask_b32_e32 v86, v86, v228, vcc
	s_and_b64 vcc, vcc, s[70:71]
	v_cndmask_b32_e32 v85, v85, v228, vcc
	s_and_b64 vcc, vcc, s[4:5]
	v_cmp_gt_i32_e64 s[68:69], 58, v64
	v_cndmask_b32_e32 v84, v84, v228, vcc
	v_cmp_gt_i32_e32 vcc, 59, v64
	v_cmp_gt_i32_e64 s[66:67], 57, v64
	v_cmp_gt_i32_e64 s[64:65], 56, v64
	v_cndmask_b32_e32 v83, v83, v228, vcc
	s_and_b64 vcc, vcc, s[68:69]
	v_cndmask_b32_e32 v82, v82, v228, vcc
	s_and_b64 vcc, vcc, s[66:67]
	v_cmp_gt_i32_e64 s[62:63], 51, v64
	v_cndmask_b32_e32 v81, v81, v228, vcc
	s_and_b64 vcc, vcc, s[64:65]
	v_cmp_gt_i32_e64 s[60:61], 50, v64
	v_cndmask_b32_e32 v80, v80, v228, vcc
	s_and_b64 vcc, vcc, s[62:63]
	v_cmp_gt_i32_e64 s[58:59], 49, v64
	v_cndmask_b32_e32 v79, v79, v228, vcc
	s_and_b64 vcc, vcc, s[60:61]
	v_cmp_gt_i32_e64 s[56:57], 48, v64
	v_cndmask_b32_e32 v78, v78, v228, vcc
	s_and_b64 vcc, vcc, s[58:59]
	v_cmp_gt_i32_e64 s[54:55], 43, v64
	v_cndmask_b32_e32 v77, v77, v228, vcc
	s_and_b64 vcc, vcc, s[56:57]
	v_cmp_gt_i32_e64 s[52:53], 42, v64
	v_cndmask_b32_e32 v76, v76, v228, vcc
	s_and_b64 vcc, vcc, s[54:55]
	v_cmp_gt_i32_e64 s[50:51], 41, v64
	v_cndmask_b32_e32 v75, v75, v228, vcc
	s_and_b64 vcc, vcc, s[52:53]
	v_cmp_gt_i32_e64 s[46:47], 40, v64
	v_cndmask_b32_e32 v74, v74, v228, vcc
	s_and_b64 vcc, vcc, s[50:51]
	v_cmp_gt_i32_e64 s[44:45], 35, v64
	v_cndmask_b32_e32 v73, v73, v228, vcc
	s_and_b64 vcc, vcc, s[46:47]
	v_cmp_gt_i32_e64 s[42:43], 34, v64
	v_cndmask_b32_e32 v72, v72, v228, vcc
	s_and_b64 vcc, vcc, s[44:45]
	v_cmp_gt_i32_e64 s[0:1], 33, v64
	v_cndmask_b32_e32 v71, v71, v228, vcc
	s_and_b64 vcc, vcc, s[42:43]
	v_cmp_gt_i32_e64 s[6:7], 32, v64
	v_cndmask_b32_e32 v70, v70, v228, vcc
	s_and_b64 vcc, vcc, s[0:1]
	v_cndmask_b32_e32 v69, v69, v228, vcc
	s_and_b64 vcc, vcc, s[6:7]
	s_mov_b32 s97, 0x41000000
	v_cndmask_b32_e32 v68, v68, v228, vcc

; __device__ __forceinline__ void finishSM(f32x16& p0, f32x16& p1, float alpha, float& l_reg, bf16x8& pa0, bf16x8& pa1, bf16x8& pa2, bf16x8& pa3) {
; #pragma unroll
;     for (int r = 0; r < 16; ++r) p1[r] = __builtin_amdgcn_exp2f(p1[r]);
;     float ps = 0;
; #pragma unroll
;     for (int r = 0; r < 16; ++r) ps += p0[r];
; #pragma unroll
;     for (int r = 0; r < 16; ++r) ps += p1[r];
;     { auto rr = __builtin_amdgcn_permlane32_swap(__float_as_uint(ps), __float_as_uint(ps), false, false);
;       ps = __uint_as_float(rr[0]) + __uint_as_float(rr[1]); }
;     l_reg = l_reg * alpha + ps;
;     ...
;     PK4(p0, 0, pa0); PK4(p0, 8, pa1); PK4(p1, 0, pa2); PK4(p1, 8, pa3);
;     ...
; }
; template <int KB>
; __device__ __forceinline__ void qkt(f32x16& p0, f32x16& p1, const char* K_lds, int r32, int hi, const bf16x8* qr, const char* qbase) {
;     p0 = f32x16{}; p1 = f32x16{};
;     const char* kbp = K_lds + KB * SHM_K + r32 * KROW + hi * 16;
; #pragma unroll
;     for (int d0 = 0; d0 < 12; ++d0) { const char* a = kbp + d0 * 32;
;         bf16x8 b0 = *reinterpret_cast<const bf16x8*>(a);
;         bf16x8 b1 = *reinterpret_cast<const bf16x8*>(a + 32 * KROW);
;         const bf16x8 qf = d0 < 4 ? qr[d0 & 3] : *reinterpret_cast<const bf16x8*>(qbase + (d0 - 4) * 32);
;         p0 = __builtin_amdgcn_mfma_f32_32x32x16_bf16(b0, qf, p0, 0, 0, 0);
;         p1 = __builtin_amdgcn_mfma_f32_32x32x16_bf16(b1, qf, p1, 0, 0, 0); }
; }
.La_s3skip2:
	v_exp_f32_e32 v85, v85
	v_exp_f32_e32 v86, v86
	v_exp_f32_e32 v87, v87
	s_waitcnt lgkmcnt(1)
	v_mfma_f32_32x32x16_bf16 v[112:127], v[96:99], v[142:145], 0
	v_exp_f32_e32 v88, v88
	v_exp_f32_e32 v89, v89
	v_exp_f32_e32 v90, v90
	v_exp_f32_e32 v91, v91
	v_exp_f32_e32 v92, v92
	v_mfma_f32_32x32x16_bf16 v[96:111], v[80:83], v[142:145], 0
	ds_read_b128 v[80:83], v202 offset:45600
	s_waitcnt lgkmcnt(1)
	v_mfma_f32_32x32x16_bf16 v[112:127], v[170:173], v[138:141], v[112:127]
	v_exp_f32_e32 v253, v95
	v_exp_f32_e32 v95, v166
	v_exp_f32_e32 v250, v84
	s_waitcnt lgkmcnt(0)
	v_mfma_f32_32x32x16_bf16 v[96:111], v[80:83], v[138:141], v[96:111]
	ds_read_b128 v[80:83], v202 offset:32832
	ds_read_b128 v[170:173], v202 offset:45632
	v_exp_f32_e32 v251, v93
	v_exp_f32_e32 v252, v94
	v_exp_f32_e32 v84, v167
	s_waitcnt lgkmcnt(1)
	v_mfma_f32_32x32x16_bf16 v[112:127], v[80:83], v[134:137], v[112:127]
	v_exp_f32_e32 v93, v168
	v_exp_f32_e32 v94, v169
	v_add_f32_e32 v255, 0, v64
	s_waitcnt lgkmcnt(0)
	v_mfma_f32_32x32x16_bf16 v[96:111], v[170:173], v[134:137], v[96:111]
	ds_read_b128 v[80:83], v202 offset:32864
	ds_read_b128 v[170:173], v202 offset:45664
	v_add_f32_e32 v255, v65, v255
	v_add_f32_e32 v255, v66, v255
	v_add_f32_e32 v255, v67, v255
	s_waitcnt lgkmcnt(1)
	v_mfma_f32_32x32x16_bf16 v[112:127], v[80:83], v[130:133], v[112:127]
	v_add_f32_e32 v255, v68, v255
	v_add_f32_e32 v255, v69, v255
	v_add_f32_e32 v255, v70, v255
	s_waitcnt lgkmcnt(0)
	v_mfma_f32_32x32x16_bf16 v[96:111], v[170:173], v[130:133], v[96:111]
	ds_read_b128 v[80:83], v202 offset:32896
	ds_read_b128 v[170:173], v202 offset:45696
	ds_read_b128 v[174:177], v201
	ds_read_b128 v[178:181], v201 offset:32
	v_add_f32_e32 v255, v71, v255
	v_add_f32_e32 v255, v72, v255
	v_add_f32_e32 v255, v73, v255
	s_waitcnt lgkmcnt(1)
	v_mfma_f32_32x32x16_bf16 v[112:127], v[80:83], v[174:177], v[112:127]
	v_mfma_f32_32x32x16_bf16 v[96:111], v[170:173], v[174:177], v[96:111]
	ds_read_b128 v[80:83], v202 offset:32928
	ds_read_b128 v[170:173], v202 offset:45728
	v_add_f32_e32 v255, v74, v255
	v_add_f32_e32 v255, v75, v255
	v_add_f32_e32 v255, v76, v255
	s_waitcnt lgkmcnt(1)
	v_mfma_f32_32x32x16_bf16 v[112:127], v[80:83], v[178:181], v[112:127]
	v_add_f32_e32 v255, v77, v255
	v_add_f32_e32 v255, v78, v255
	v_add_f32_e32 v255, v79, v255
	s_waitcnt lgkmcnt(0)
	v_mfma_f32_32x32x16_bf16 v[96:111], v[170:173], v[178:181], v[96:111]
	ds_read_b128 v[80:83], v202 offset:32960
	ds_read_b128 v[170:173], v202 offset:45760
	ds_read_b128 v[174:177], v201 offset:64
	v_add_f32_e32 v255, v85, v255
	v_add_f32_e32 v255, v86, v255
	v_add_f32_e32 v255, v87, v255
	s_waitcnt lgkmcnt(0)
	v_mfma_f32_32x32x16_bf16 v[112:127], v[80:83], v[174:177], v[112:127]
	v_mfma_f32_32x32x16_bf16 v[96:111], v[170:173], v[174:177], v[96:111]
	ds_read_b128 v[80:83], v202 offset:32992
	ds_read_b128 v[170:173], v202 offset:45792
	ds_read_b128 v[174:177], v201 offset:96
	v_add_f32_e32 v255, v88, v255
	v_add_f32_e32 v255, v89, v255
	v_add_f32_e32 v255, v90, v255
	s_waitcnt lgkmcnt(0)
	v_mfma_f32_32x32x16_bf16 v[112:127], v[80:83], v[174:177], v[112:127]
	v_mfma_f32_32x32x16_bf16 v[96:111], v[170:173], v[174:177], v[96:111]
	ds_read_b128 v[80:83], v202 offset:33024
	ds_read_b128 v[170:173], v202 offset:45824
	ds_read_b128 v[174:177], v201 offset:128
	v_add_f32_e32 v255, v91, v255
	v_add_f32_e32 v255, v92, v255
	v_add_f32_e32 v255, v250, v255
	s_waitcnt lgkmcnt(0)
	v_mfma_f32_32x32x16_bf16 v[112:127], v[80:83], v[174:177], v[112:127]
	v_mfma_f32_32x32x16_bf16 v[96:111], v[170:173], v[174:177], v[96:111]
	ds_read_b128 v[80:83], v202 offset:33056
	ds_read_b128 v[170:173], v202 offset:45856
	ds_read_b128 v[174:177], v201 offset:160
	v_add_f32_e32 v255, v251, v255
	v_add_f32_e32 v255, v252, v255
	v_add_f32_e32 v255, v253, v255
	s_waitcnt lgkmcnt(0)
	v_mfma_f32_32x32x16_bf16 v[112:127], v[80:83], v[174:177], v[112:127]
	v_mfma_f32_32x32x16_bf16 v[96:111], v[170:173], v[174:177], v[96:111]
	ds_read_b128 v[80:83], v202 offset:33088
	ds_read_b128 v[170:173], v202 offset:45888
	ds_read_b128 v[174:177], v201 offset:192
	v_add_f32_e32 v255, v84, v255
	v_add_f32_e32 v255, v93, v255
	v_add_f32_e32 v255, v94, v255
	s_waitcnt lgkmcnt(0)
	v_mfma_f32_32x32x16_bf16 v[112:127], v[80:83], v[174:177], v[112:127]
	v_mfma_f32_32x32x16_bf16 v[96:111], v[170:173], v[174:177], v[96:111]
	ds_read_b128 v[80:83], v202 offset:33120
	ds_read_b128 v[170:173], v202 offset:45920
	ds_read_b128 v[174:177], v201 offset:224
	v_add_f32_e32 v236, v95, v255
	s_waitcnt lgkmcnt(0)
	v_mfma_f32_32x32x16_bf16 v[112:127], v[80:83], v[174:177], v[112:127]
	v_mfma_f32_32x32x16_bf16 v[96:111], v[170:173], v[174:177], v[96:111]
	v_mov_b32_e32 v237, v236
	v_cvt_pk_bf16_f32 v166, v64, v65
	v_cvt_pk_bf16_f32 v167, v66, v67
	v_cvt_pk_bf16_f32 v168, v68, v69
	v_cvt_pk_bf16_f32 v169, v70, v71
	v_cvt_pk_bf16_f32 v170, v72, v73
	v_cvt_pk_bf16_f32 v171, v74, v75
	v_cvt_pk_bf16_f32 v172, v76, v77
	v_cvt_pk_bf16_f32 v173, v78, v79
	v_cvt_pk_bf16_f32 v174, v250, v251
	v_cvt_pk_bf16_f32 v175, v252, v253
	v_cvt_pk_bf16_f32 v176, v84, v85
	v_cvt_pk_bf16_f32 v177, v86, v87
	v_cvt_pk_bf16_f32 v178, v88, v89
	v_cvt_pk_bf16_f32 v179, v90, v91
	v_cvt_pk_bf16_f32 v180, v92, v93
	v_cvt_pk_bf16_f32 v181, v94, v95
	s_nop 1
	v_permlane32_swap_b32_e32 v236, v237
	v_permlane32_swap_b32_e32 v166, v168
	v_permlane32_swap_b32_e32 v167, v169
	v_permlane32_swap_b32_e32 v170, v172
	v_permlane32_swap_b32_e32 v171, v173
	v_permlane32_swap_b32_e32 v174, v176
	v_permlane32_swap_b32_e32 v175, v177
	v_permlane32_swap_b32_e32 v178, v180
	v_permlane32_swap_b32_e32 v179, v181
